# v027: prologue weight-transpose loop keeps two tiles in flight (destination sets alternate by tile parity, address temps moved, extra scalar stage, priming pass)
# baseline (speedup 1.0000x reference)
.Lpro_lds:
	s_lshl_b64 s[0:1], s[8:9], 1
	s_add_u32 s0, s4, s0
	s_addc_u32 s1, s5, s1
	v_add_u32_e32 v6, s27, v33
	ds_write_b16 v42, v0 offset:492
	s_waitcnt lgkmcnt(0)
	s_barrier
	v_lshl_add_u64 v[4:5], s[0:1], 0, v[192:193]
	ds_read2_b32 v[0:1], v40 offset1:1
	ds_read2_b32 v[2:3], v40 offset0:2 offset1:3
	v_ashrrev_i32_e32 v9, 31, v6
	v_mad_u64_u32 v[6:7], s[0:1], v6, s26, 0
	v_mov_b32_e32 v8, v7
	v_mad_u64_u32 v[8:9], s[0:1], v9, s26, v[8:9]
	v_mov_b32_e32 v7, v8
	v_lshl_add_u64 v[6:7], v[6:7], 1, v[4:5]
	s_waitcnt lgkmcnt(0)
	global_store_dwordx4 v[6:7], v[0:3], off
	v_add_u32_e32 v6, s27, v39
	ds_read2_b32 v[0:1], v41 offset1:1
	ds_read2_b32 v[2:3], v41 offset0:2 offset1:3
	v_ashrrev_i32_e32 v9, 31, v6
	v_mad_u64_u32 v[6:7], s[0:1], v6, s26, 0
	v_mov_b32_e32 v8, v7
	v_mad_u64_u32 v[8:9], s[0:1], v9, s26, v[8:9]
	v_mov_b32_e32 v7, v8
	v_lshl_add_u64 v[4:5], v[6:7], 1, v[4:5]
	s_waitcnt lgkmcnt(0)
	global_store_dwordx4 v[4:5], v[0:3], off
	s_bitcmp1_b32 s25, 8
	s_cbranch_scc1 .Ltr_cpA
	v_mov_b64_e32 v[12:13], v[86:87]
	v_mov_b64_e32 v[8:9], v[82:83]
	v_mov_b64_e32 v[4:5], v[94:95]
	v_mov_b64_e32 v[0:1], v[90:91]
	v_mov_b64_e32 v[14:15], v[88:89]
	v_mov_b64_e32 v[10:11], v[84:85]
	v_mov_b64_e32 v[6:7], v[96:97]
	v_mov_b64_e32 v[2:3], v[92:93]
	s_branch .Ltr_cpdone
.Ltr_cpA:
	v_mov_b64_e32 v[12:13], v[20:21]
	v_mov_b64_e32 v[8:9], v[16:17]
	v_mov_b64_e32 v[4:5], v[28:29]
	v_mov_b64_e32 v[0:1], v[24:25]
	v_mov_b64_e32 v[14:15], v[22:23]
	v_mov_b64_e32 v[10:11], v[18:19]
	v_mov_b64_e32 v[6:7], v[30:31]
	v_mov_b64_e32 v[2:3], v[26:27]
.Ltr_cpdone:
	s_mov_b32 s6, s17
	s_mov_b32 s7, s32
	s_mov_b32 s4, s73
	s_mov_b32 s5, s74
	s_mov_b32 s26, s77
	s_mov_b32 s8, s98
	s_mov_b32 s27, s99
	s_mov_b32 s17, s14
	s_mov_b32 s32, s15
	s_mov_b32 s73, s12
	s_mov_b32 s74, s13
	s_mov_b32 s77, s49
	s_mov_b32 s98, s23
	s_mov_b32 s99, s22
	s_sub_i32 s0, s25, s70
	s_cmpk_gt_i32 s0, 0x167f
	s_waitcnt lgkmcnt(0)
	s_barrier
	s_cbranch_scc1 .LBB0_842

.LBB0_809:
	s_lshr_b32 s22, s50, 7
	v_cvt_f32_i32_e32 v102, s22
	s_sext_i32_i16 s9, s51
	v_cvt_f32_i32_e32 v103, s9
	s_ashr_i32 s9, s9, 30
	v_rcp_iflag_f32_e32 v104, v102
	s_or_b32 s9, s9, 1
	v_mul_f32_e32 v104, v103, v104
	v_trunc_f32_e32 v104, v104
	v_fma_f32 v103, -v104, v102, v103
	v_cvt_i32_f32_e32 v104, v104
	v_cmp_ge_f32_e64 s[20:21], |v103|, v102
	s_and_b64 s[20:21], s[20:21], exec
	s_cselect_b32 s9, s9, 0
	v_readfirstlane_b32 s20, v104
	s_add_i32 s9, s20, s9
	s_mul_i32 s20, s9, s22
	s_sub_i32 s20, s51, s20
	s_sext_i32_i16 s21, s20
	s_lshl_b32 s20, s21, 7
	s_andn2_b64 vcc, exec, s[18:19]
	s_mov_b32 s22, s20
	s_cbranch_vccnz .LBB0_830
	s_cmp_lt_i32 s21, 4
	s_cbranch_scc1 .LBB0_829
	s_and_b32 s23, s21, 0xffff
	s_cmp_gt_u32 s23, 7
	s_mov_b64 s[18:19], -1
	s_cbranch_scc0 .LBB0_826
	s_cmp_gt_u32 s23, 11
	s_cbranch_scc0 .LBB0_823
	s_cmp_gt_u32 s23, 15
	s_cbranch_scc0 .LBB0_820
	s_cmp_lt_u32 s23, 24
	s_mov_b32 s22, s21
	s_cbranch_scc1 .LBB0_819
	s_cmp_gt_u32 s23, 27
	s_cbranch_scc0 .LBB0_817
	s_lshl_b32 s18, s21, 1
	s_sub_i32 s18, s18, 31
	s_cmp_lt_u32 s23, 32
	s_cselect_b32 s22, s18, s21
	s_mov_b64 s[18:19], 0

.LBB0_830:
	s_sext_i32_i16 s9, s9
	s_ashr_i32 s21, s20, 31
	s_lshl_b32 s23, s9, 6
	s_lshl_b64 s[18:19], s[20:21], 2
	v_add_u32_e32 v116, s23, v34
	s_add_u32 s0, s0, s18
	s_addc_u32 s1, s1, s19
	v_mov_b32_e32 v37, v193
	v_add_u32_e32 v112, 32, v116
	v_lshl_add_u64 v[110:111], s[0:1], 0, v[36:37]
	v_mad_u64_u32 v[102:103], s[0:1], v116, s50, 0
	v_ashrrev_i32_e32 v115, 31, v112
	v_mad_u64_u32 v[112:113], s[0:1], v112, s50, 0
	v_ashrrev_i32_e32 v105, 31, v116
	v_mov_b32_e32 v104, v103
	v_mov_b32_e32 v114, v113
	v_mad_u64_u32 v[104:105], s[0:1], v105, s50, v[104:105]
	v_mad_u64_u32 v[114:115], s[0:1], v115, s50, v[114:115]
	v_mov_b32_e32 v103, v104
	v_add_u32_e32 v104, 16, v116
	v_mov_b32_e32 v113, v114
	v_add_u32_e32 v114, 48, v116
	v_ashrrev_i32_e32 v107, 31, v104
	v_mad_u64_u32 v[104:105], s[0:1], v104, s50, 0
	v_ashrrev_i32_e32 v117, 31, v114
	v_mad_u64_u32 v[114:115], s[0:1], v114, s50, 0
	v_mov_b32_e32 v106, v105
	v_mov_b32_e32 v116, v115
	v_mad_u64_u32 v[106:107], s[0:1], v107, s50, v[106:107]
	v_mad_u64_u32 v[116:117], s[0:1], v117, s50, v[116:117]
	v_mov_b32_e32 v105, v106
	v_mov_b32_e32 v115, v116
	v_lshl_add_u64 v[102:103], v[102:103], 2, v[110:111]
	v_lshl_add_u64 v[104:105], v[104:105], 2, v[110:111]
	v_lshl_add_u64 v[112:113], v[112:113], 2, v[110:111]
	v_lshl_add_u64 v[110:111], v[114:115], 2, v[110:111]
	s_bitcmp1_b32 s25, 8
	s_cbranch_scc1 .Ltr_ldB
	global_load_dwordx4 v[20:23], v[102:103], off
	global_load_dwordx4 v[16:19], v[104:105], off
	global_load_dwordx4 v[28:31], v[112:113], off
	global_load_dwordx4 v[24:27], v[110:111], off
	s_branch .LBB0_831
.Ltr_ldB:
	global_load_dwordx4 v[86:89], v[102:103], off
	global_load_dwordx4 v[82:85], v[104:105], off
	global_load_dwordx4 v[94:97], v[112:113], off
	global_load_dwordx4 v[90:93], v[110:111], off
.LBB0_831:
	s_cmpk_lt_u32 s25, 0x200
	s_cbranch_scc1 .Ltr_prime_done
	s_waitcnt vmcnt(4)
	s_branch .Lpro_body
.Lpro_nonext:
	s_cmpk_lt_u32 s25, 0x200
	s_cbranch_scc1 .Ltr_prime_done
	s_waitcnt vmcnt(0)
	s_branch .Lpro_body
.Ltr_prime_done:
	s_mov_b32 s17, s14
	s_mov_b32 s32, s15
	s_mov_b32 s73, s12
	s_mov_b32 s74, s13
	s_mov_b32 s77, s49
	s_mov_b32 s98, s23
	s_mov_b32 s99, s22
	s_branch .LBB0_778
